# G1 epilogue: rope cos/sin table rows loaded once per row group together with the sum-of-squares loads (was twice per group with exposed latency)
# baseline (speedup 1.0000x reference)
.LBB0_175:
	v_ashrrev_i32_e32 v185, 31, v184
	v_lshlrev_b64 v[190:191], 6, v[184:185]
	v_lshl_add_u64 v[160:161], s[12:13], 0, v[190:191]
	global_load_dwordx4 v[218:221], v190, s[14:15] offset:32
	global_load_dwordx4 v[222:225], v190, s[14:15] offset:48
	global_load_dwordx4 v[226:229], v190, s[14:15]
	global_load_dwordx4 v[230:233], v190, s[14:15] offset:16
	global_load_dwordx4 v[186:189], v[160:161], off offset:16
	global_load_dwordx4 v[192:195], v[160:161], off offset:48
	global_load_dwordx4 v[196:199], v[160:161], off
	global_load_dwordx4 v[200:203], v[160:161], off offset:32
	s_cmp_lt_i32 s61, 4
	s_cselect_b64 s[34:35], -1, 0
	s_waitcnt vmcnt(0)
	v_mov_b32_e32 v164, v188
	v_mov_b32_e32 v165, v194
	v_mov_b32_e32 v160, v196
	v_mov_b32_e32 v161, v200
	v_mov_b32_e32 v200, v197
	v_mov_b32_e32 v162, v198
	v_mov_b32_e32 v163, v202
	v_mov_b32_e32 v202, v199
	v_pk_add_f32 v[160:161], v[160:161], v[200:201]
	v_pk_add_f32 v[162:163], v[162:163], v[202:203]
	v_mov_b32_e32 v194, v189
	v_pk_add_f32 v[160:161], v[160:161], v[162:163]
	v_mov_b32_e32 v162, v186
	v_mov_b32_e32 v163, v192
	v_mov_b32_e32 v192, v187
	v_pk_add_f32 v[162:163], v[162:163], v[192:193]
	v_pk_add_f32 v[164:165], v[164:165], v[194:195]
	s_nop 0
	v_pk_add_f32 v[162:163], v[162:163], v[164:165]
	s_nop 0
	v_pk_add_f32 v[160:161], v[160:161], v[162:163]
	s_nop 0
	v_add_f32_e32 v160, v160, v161
	v_fmamk_f32 v160, v160, 0x3a800000, v208
	v_cmp_gt_f32_e32 vcc, s94, v160
	v_mul_f32_e32 v161, 0x4b800000, v160
	s_nop 0
	v_cndmask_b32_e32 v160, v160, v161, vcc
	v_rsq_f32_e32 v160, v160
	s_nop 0
	v_mul_f32_e32 v161, 0x45800000, v160
	v_cndmask_b32_e32 v192, v160, v161, vcc
	v_cndmask_b32_e64 v160, 0, 1, s[18:19]
	v_pk_fma_f32 v[200:201], v[78:79], v[192:193], v[30:31] op_sel_hi:[1,0,1]
	v_pk_fma_f32 v[198:199], v[76:77], v[192:193], v[28:29] op_sel_hi:[1,0,1]
	v_pk_fma_f32 v[196:197], v[74:75], v[192:193], v[26:27] op_sel_hi:[1,0,1]
	v_pk_fma_f32 v[194:195], v[72:73], v[192:193], v[24:25] op_sel_hi:[1,0,1]
	v_cmp_ne_u32_e64 s[44:45], 1, v160
	s_andn2_b64 vcc, exec, s[18:19]
	s_cbranch_vccnz .LBB0_180
	s_add_i32 s25, s61, -6
	s_cmp_gt_u32 s25, 2
	s_cselect_b64 s[36:37], -1, 0
	s_xor_b64 s[38:39], s[34:35], -1
	s_and_b64 s[36:37], s[38:39], s[36:37]
	s_and_b64 vcc, exec, s[36:37]
	s_cbranch_vccnz .LBB0_180
	v_mbcnt_hi_u32_b32 v160, -1, v207
	v_and_b32_e32 v162, 64, v160
	v_xor_b32_e32 v161, 16, v160
	v_add_u32_e32 v162, 64, v162
	v_cmp_lt_i32_e32 vcc, v161, v162
	s_nop 1
	v_cndmask_b32_e32 v160, v160, v161, vcc
	v_lshlrev_b32_e32 v160, 2, v160
	ds_bpermute_b32 v202, v160, v198
	ds_bpermute_b32 v186, v160, v194
	ds_bpermute_b32 v203, v160, v199
	ds_bpermute_b32 v187, v160, v195
	ds_bpermute_b32 v204, v160, v200
	ds_bpermute_b32 v188, v160, v196
	ds_bpermute_b32 v205, v160, v201
	ds_bpermute_b32 v189, v160, v197
	s_and_saveexec_b64 s[36:37], s[40:41]
	s_cbranch_execz .LBB0_179
	s_waitcnt lgkmcnt(1)
	v_pk_mul_f32 v[160:161], v[220:221], v[204:205]
	v_pk_mul_f32 v[162:163], v[218:219], v[202:203]
	s_waitcnt lgkmcnt(0)
	v_pk_mul_f32 v[164:165], v[224:225], v[188:189]
	v_pk_mul_f32 v[186:187], v[222:223], v[186:187]
	v_pk_mul_f32 v[162:163], v[174:175], v[162:163]
	v_pk_mul_f32 v[160:161], v[176:177], v[160:161]
	v_pk_mul_f32 v[186:187], v[174:175], v[186:187]
	v_pk_mul_f32 v[164:165], v[176:177], v[164:165]
	v_pk_fma_f32 v[200:201], v[200:201], v[228:229], v[160:161]
	v_pk_fma_f32 v[198:199], v[198:199], v[226:227], v[162:163]
	v_pk_fma_f32 v[196:197], v[196:197], v[232:233], v[164:165]
	v_pk_fma_f32 v[194:195], v[194:195], v[230:231], v[186:187]

.LBB0_180:
	s_cmp_lt_i32 s61, 2
	v_add_u32_e32 v160, s23, v215
	s_cselect_b64 s[36:37], -1, 0
	s_and_b32 s23, s61, -2
	s_cmp_eq_u32 s23, 6
	s_cselect_b64 s[38:39], -1, 0
	s_or_b64 vcc, s[36:37], s[38:39]
	v_ashrrev_i32_e32 v161, 31, v160
	s_waitcnt lgkmcnt(6)
	v_cndmask_b32_e32 v186, 1.0, v212, vcc
	s_waitcnt lgkmcnt(0)
	v_lshl_add_u64 v[188:189], v[160:161], 1, s[0:1]
	v_mad_i64_i32 v[160:161], s[36:37], s30, v184, 0
	s_or_b64 s[0:1], s[34:35], s[38:39]
	v_lshl_add_u64 v[202:203], v[160:161], 1, v[188:189]
	v_pk_mul_f32 v[160:161], v[186:187], v[200:201] op_sel_hi:[0,1]
	v_pk_mul_f32 v[162:163], v[186:187], v[198:199] op_sel_hi:[0,1]
	v_pk_mul_f32 v[164:165], v[186:187], v[196:197] op_sel_hi:[0,1]
	v_pk_mul_f32 v[196:197], v[186:187], v[194:195] op_sel_hi:[0,1]
	v_cvt_pk_bf16_f32 v194, v162, v163
	v_cvt_pk_bf16_f32 v195, v160, v161
	v_cvt_pk_bf16_f32 v196, v196, v197
	v_cvt_pk_bf16_f32 v197, v164, v165
	v_mov_b32_e32 v160, v192
	v_mov_b32_e32 v161, v192
	s_and_b64 s[0:1], s[18:19], s[0:1]
	v_mov_b32_e32 v193, v192
	global_store_dwordx4 v[202:203], v[194:197], off
	v_pk_fma_f32 v[150:151], v[150:151], v[160:161], v[110:111]
	v_pk_fma_f32 v[148:149], v[148:149], v[192:193], v[108:109]
	v_pk_fma_f32 v[194:195], v[146:147], v[160:161], v[106:107]
	v_cndmask_b32_e64 v146, 0, 1, s[0:1]
	v_cmp_ne_u32_e64 s[46:47], 1, v146
	s_andn2_b64 vcc, exec, s[0:1]
	v_pk_fma_f32 v[144:145], v[144:145], v[192:193], v[104:105]
	s_cbranch_vccnz .LBB0_184
	v_mbcnt_hi_u32_b32 v146, -1, v207
	v_and_b32_e32 v160, 64, v146
	v_xor_b32_e32 v147, 16, v146
	v_add_u32_e32 v160, 64, v160
	v_cmp_lt_i32_e32 vcc, v147, v160
	s_nop 1
	v_cndmask_b32_e32 v146, v146, v147, vcc
	v_lshlrev_b32_e32 v160, 2, v146
	ds_bpermute_b32 v196, v160, v148
	ds_bpermute_b32 v146, v160, v144
	ds_bpermute_b32 v197, v160, v149
	ds_bpermute_b32 v147, v160, v145
	ds_bpermute_b32 v198, v160, v150
	ds_bpermute_b32 v192, v160, v194
	ds_bpermute_b32 v199, v160, v151
	ds_bpermute_b32 v193, v160, v195
	s_and_saveexec_b64 s[0:1], s[40:41]
	s_cbranch_execz .LBB0_183
	s_waitcnt lgkmcnt(1)
	v_pk_mul_f32 v[160:161], v[220:221], v[198:199]
	v_pk_mul_f32 v[162:163], v[218:219], v[196:197]
	s_waitcnt lgkmcnt(0)
	v_pk_mul_f32 v[164:165], v[224:225], v[192:193]
	v_pk_mul_f32 v[146:147], v[222:223], v[146:147]
	v_pk_mul_f32 v[162:163], v[174:175], v[162:163]
	v_pk_mul_f32 v[160:161], v[176:177], v[160:161]
	v_pk_mul_f32 v[146:147], v[174:175], v[146:147]
	v_pk_mul_f32 v[164:165], v[176:177], v[164:165]
	v_pk_fma_f32 v[150:151], v[150:151], v[228:229], v[160:161]
	v_pk_fma_f32 v[148:149], v[148:149], v[226:227], v[162:163]
	v_pk_fma_f32 v[194:195], v[194:195], v[232:233], v[164:165]
	v_pk_fma_f32 v[144:145], v[144:145], v[230:231], v[146:147]

.LBB0_184:
	v_mov_b32_e32 v187, v186
	s_waitcnt lgkmcnt(6)
	v_mov_b32_e32 v146, v186
	s_waitcnt lgkmcnt(4)
	v_mov_b32_e32 v147, v186
	v_pk_mul_f32 v[150:151], v[146:147], v[150:151]
	v_pk_mul_f32 v[148:149], v[186:187], v[148:149]
	v_pk_mul_f32 v[160:161], v[146:147], v[194:195]
	v_pk_mul_f32 v[144:145], v[186:187], v[144:145]
	v_cvt_pk_bf16_f32 v148, v148, v149
	v_cvt_pk_bf16_f32 v149, v150, v151
	v_cvt_pk_bf16_f32 v150, v144, v145
	v_cvt_pk_bf16_f32 v151, v160, v161
	global_store_dwordx4 v[202:203], v[148:151], off offset:256
	s_and_b64 vcc, exec, s[44:45]
	s_nop 0
	v_add_u32_e32 v148, 16, v184
	v_ashrrev_i32_e32 v149, 31, v148
	v_lshlrev_b64 v[144:145], 6, v[148:149]
	v_lshl_add_u64 v[150:151], s[12:13], 0, v[144:145]
	global_load_dwordx4 v[218:221], v144, s[14:15] offset:32
	global_load_dwordx4 v[222:225], v144, s[14:15] offset:48
	global_load_dwordx4 v[226:229], v144, s[14:15]
	global_load_dwordx4 v[230:233], v144, s[14:15] offset:16
	s_waitcnt lgkmcnt(0)
	global_load_dwordx4 v[190:193], v[150:151], off
	global_load_dwordx4 v[194:197], v[150:151], off offset:32
	global_load_dwordx4 v[198:201], v[150:151], off offset:16
	global_load_dwordx4 v[202:205], v[150:151], off offset:48
	s_waitcnt vmcnt(3)
	v_mov_b32_e32 v150, v190
	s_waitcnt vmcnt(2)
	v_mov_b32_e32 v151, v194
	v_mov_b32_e32 v194, v191
	v_mov_b32_e32 v160, v192
	v_mov_b32_e32 v161, v196
	v_mov_b32_e32 v196, v193
	s_waitcnt vmcnt(1)
	v_mov_b32_e32 v162, v198
	s_waitcnt vmcnt(0)
	v_mov_b32_e32 v163, v202
	v_mov_b32_e32 v202, v199
	v_mov_b32_e32 v164, v200
	v_mov_b32_e32 v165, v204
	v_mov_b32_e32 v204, v201
	v_pk_add_f32 v[150:151], v[150:151], v[194:195]
	v_pk_add_f32 v[160:161], v[160:161], v[196:197]
	v_pk_add_f32 v[162:163], v[162:163], v[202:203]
	v_pk_add_f32 v[164:165], v[164:165], v[204:205]
	v_pk_add_f32 v[150:151], v[150:151], v[160:161]
	v_pk_add_f32 v[160:161], v[162:163], v[164:165]
	s_nop 0
	v_pk_add_f32 v[150:151], v[150:151], v[160:161]
	s_nop 0
	v_add_f32_e32 v149, v150, v151
	v_fmamk_f32 v149, v149, 0x3a800000, v208
	v_mul_f32_e32 v150, 0x4b800000, v149
	v_cmp_gt_f32_e64 s[0:1], s94, v149
	s_nop 1
	v_cndmask_b32_e64 v149, v149, v150, s[0:1]
	v_rsq_f32_e32 v149, v149
	s_nop 0
	v_mul_f32_e32 v150, 0x45800000, v149
	v_cndmask_b32_e64 v150, v149, v150, s[0:1]
	v_pk_fma_f32 v[196:197], v[70:71], v[150:151], v[30:31] op_sel_hi:[1,0,1]
	v_pk_fma_f32 v[194:195], v[68:69], v[150:151], v[28:29] op_sel_hi:[1,0,1]
	v_pk_fma_f32 v[192:193], v[66:67], v[150:151], v[26:27] op_sel_hi:[1,0,1]
	v_pk_fma_f32 v[190:191], v[64:65], v[150:151], v[24:25] op_sel_hi:[1,0,1]
	s_cbranch_vccnz .LBB0_189
	s_add_i32 s0, s61, -6
	s_cmp_gt_u32 s0, 2
	s_cselect_b64 s[0:1], -1, 0
	s_xor_b64 s[36:37], s[34:35], -1
	s_and_b64 s[0:1], s[36:37], s[0:1]
	s_and_b64 vcc, exec, s[0:1]
	s_cbranch_vccnz .LBB0_189
	v_mbcnt_hi_u32_b32 v149, -1, v207
	v_and_b32_e32 v160, 64, v149
	v_xor_b32_e32 v151, 16, v149
	v_add_u32_e32 v160, 64, v160
	v_cmp_lt_i32_e32 vcc, v151, v160
	s_nop 1
	v_cndmask_b32_e32 v149, v149, v151, vcc
	v_lshlrev_b32_e32 v149, 2, v149
	ds_bpermute_b32 v202, v149, v194
	ds_bpermute_b32 v198, v149, v190
	ds_bpermute_b32 v203, v149, v195
	ds_bpermute_b32 v199, v149, v191
	ds_bpermute_b32 v204, v149, v196
	ds_bpermute_b32 v200, v149, v192
	ds_bpermute_b32 v205, v149, v197
	ds_bpermute_b32 v201, v149, v193
	s_and_saveexec_b64 s[0:1], s[40:41]
	s_cbranch_execz .LBB0_188
	s_waitcnt lgkmcnt(1)
	v_pk_mul_f32 v[160:161], v[220:221], v[204:205]
	v_pk_mul_f32 v[162:163], v[218:219], v[202:203]
	s_waitcnt lgkmcnt(0)
	v_pk_mul_f32 v[164:165], v[224:225], v[200:201]
	v_pk_mul_f32 v[198:199], v[222:223], v[198:199]
	v_pk_mul_f32 v[162:163], v[174:175], v[162:163]
	v_pk_mul_f32 v[160:161], v[176:177], v[160:161]
	v_pk_mul_f32 v[198:199], v[174:175], v[198:199]
	v_pk_mul_f32 v[164:165], v[176:177], v[164:165]
	v_pk_fma_f32 v[196:197], v[196:197], v[228:229], v[160:161]
	v_pk_fma_f32 v[194:195], v[194:195], v[226:227], v[162:163]
	v_pk_fma_f32 v[192:193], v[192:193], v[232:233], v[164:165]
	v_pk_fma_f32 v[190:191], v[190:191], v[230:231], v[198:199]

.LBB0_189:
	v_pk_mul_f32 v[160:161], v[146:147], v[196:197]
	v_pk_mul_f32 v[146:147], v[146:147], v[192:193]
	v_mov_b32_e32 v151, v150
	v_mad_i64_i32 v[148:149], s[0:1], s30, v148, 0
	v_pk_mul_f32 v[162:163], v[186:187], v[194:195]
	v_pk_mul_f32 v[164:165], v[186:187], v[190:191]
	v_cvt_pk_bf16_f32 v193, v146, v147
	v_mov_b32_e32 v146, v150
	v_mov_b32_e32 v147, v150
	v_lshl_add_u64 v[148:149], v[148:149], 1, v[188:189]
	v_cvt_pk_bf16_f32 v190, v162, v163
	v_cvt_pk_bf16_f32 v191, v160, v161
	v_cvt_pk_bf16_f32 v192, v164, v165
	v_pk_fma_f32 v[142:143], v[142:143], v[146:147], v[110:111]
	v_pk_fma_f32 v[140:141], v[140:141], v[150:151], v[108:109]
	v_pk_fma_f32 v[146:147], v[138:139], v[146:147], v[106:107]
	s_and_b64 vcc, exec, s[46:47]
	v_pk_fma_f32 v[136:137], v[136:137], v[150:151], v[104:105]
	global_store_dwordx4 v[148:149], v[190:193], off
	s_cbranch_vccnz .LBB0_193
	v_mbcnt_hi_u32_b32 v138, -1, v207
	v_and_b32_e32 v150, 64, v138
	v_xor_b32_e32 v139, 16, v138
	v_add_u32_e32 v150, 64, v150
	v_cmp_lt_i32_e32 vcc, v139, v150
	s_nop 1
	v_cndmask_b32_e32 v138, v138, v139, vcc
	v_lshlrev_b32_e32 v151, 2, v138
	ds_bpermute_b32 v190, v151, v140
	ds_bpermute_b32 v138, v151, v136
	ds_bpermute_b32 v191, v151, v141
	ds_bpermute_b32 v139, v151, v137
	ds_bpermute_b32 v192, v151, v142
	ds_bpermute_b32 v150, v151, v146
	ds_bpermute_b32 v193, v151, v143
	ds_bpermute_b32 v151, v151, v147
	s_and_saveexec_b64 s[0:1], s[40:41]
	s_cbranch_execz .LBB0_192
	s_waitcnt lgkmcnt(8)
	s_waitcnt lgkmcnt(1)
	v_pk_mul_f32 v[144:145], v[220:221], v[192:193]
	v_pk_mul_f32 v[160:161], v[218:219], v[190:191]
	s_waitcnt lgkmcnt(0)
	v_pk_mul_f32 v[150:151], v[224:225], v[150:151]
	v_pk_mul_f32 v[138:139], v[222:223], v[138:139]
	v_pk_mul_f32 v[160:161], v[174:175], v[160:161]
	v_pk_mul_f32 v[144:145], v[176:177], v[144:145]
	v_pk_mul_f32 v[138:139], v[174:175], v[138:139]
	v_pk_mul_f32 v[150:151], v[176:177], v[150:151]
	v_pk_fma_f32 v[142:143], v[142:143], v[228:229], v[144:145]
	v_pk_fma_f32 v[140:141], v[140:141], v[226:227], v[160:161]
	v_pk_fma_f32 v[146:147], v[146:147], v[232:233], v[150:151]
	v_pk_fma_f32 v[136:137], v[136:137], v[230:231], v[138:139]

.LBB0_193:
	s_waitcnt lgkmcnt(6)
	v_mov_b32_e32 v138, v186
	s_waitcnt lgkmcnt(4)
	v_mov_b32_e32 v139, v186
	v_pk_mul_f32 v[142:143], v[138:139], v[142:143]
	v_pk_mul_f32 v[140:141], v[186:187], v[140:141]
	v_pk_mul_f32 v[144:145], v[138:139], v[146:147]
	v_pk_mul_f32 v[136:137], v[186:187], v[136:137]
	v_cvt_pk_bf16_f32 v140, v140, v141
	v_cvt_pk_bf16_f32 v141, v142, v143
	v_cvt_pk_bf16_f32 v142, v136, v137
	v_cvt_pk_bf16_f32 v143, v144, v145
	global_store_dwordx4 v[148:149], v[140:143], off offset:256
	s_and_b64 vcc, exec, s[44:45]
	s_nop 0
	v_add_u32_e32 v140, 32, v184
	v_ashrrev_i32_e32 v141, 31, v140
	v_lshlrev_b64 v[136:137], 6, v[140:141]
	s_waitcnt lgkmcnt(0)
	v_lshl_add_u64 v[150:151], s[12:13], 0, v[136:137]
	global_load_dwordx4 v[218:221], v136, s[14:15] offset:32
	global_load_dwordx4 v[222:225], v136, s[14:15] offset:48
	global_load_dwordx4 v[226:229], v136, s[14:15]
	global_load_dwordx4 v[230:233], v136, s[14:15] offset:16
	global_load_dwordx4 v[142:145], v[150:151], off
	global_load_dwordx4 v[146:149], v[150:151], off offset:32
	global_load_dwordx4 v[190:193], v[150:151], off offset:16
	global_load_dwordx4 v[194:197], v[150:151], off offset:48
	s_waitcnt vmcnt(3)
	v_mov_b32_e32 v150, v142
	s_waitcnt vmcnt(2)
	v_mov_b32_e32 v151, v146
	v_mov_b32_e32 v146, v143
	v_mov_b32_e32 v142, v144
	v_mov_b32_e32 v143, v148
	v_mov_b32_e32 v148, v145
	s_waitcnt vmcnt(1)
	v_mov_b32_e32 v144, v190
	s_waitcnt vmcnt(0)
	v_mov_b32_e32 v145, v194
	v_mov_b32_e32 v194, v191
	v_mov_b32_e32 v160, v192
	v_mov_b32_e32 v161, v196
	v_mov_b32_e32 v196, v193
	v_pk_add_f32 v[146:147], v[150:151], v[146:147]
	v_pk_add_f32 v[142:143], v[142:143], v[148:149]
	v_pk_add_f32 v[144:145], v[144:145], v[194:195]
	v_pk_add_f32 v[148:149], v[160:161], v[196:197]
	v_pk_add_f32 v[142:143], v[146:147], v[142:143]
	v_pk_add_f32 v[144:145], v[144:145], v[148:149]
	s_nop 0
	v_pk_add_f32 v[142:143], v[142:143], v[144:145]
	s_nop 0
	v_add_f32_e32 v141, v142, v143
	v_fmamk_f32 v141, v141, 0x3a800000, v208
	v_mul_f32_e32 v142, 0x4b800000, v141
	v_cmp_gt_f32_e64 s[0:1], s94, v141
	s_nop 1
	v_cndmask_b32_e64 v141, v141, v142, s[0:1]
	v_rsq_f32_e32 v141, v141
	s_nop 0
	v_mul_f32_e32 v142, 0x45800000, v141
	v_cndmask_b32_e64 v142, v141, v142, s[0:1]
	v_pk_fma_f32 v[150:151], v[62:63], v[142:143], v[30:31] op_sel_hi:[1,0,1]
	v_pk_fma_f32 v[148:149], v[60:61], v[142:143], v[28:29] op_sel_hi:[1,0,1]
	v_pk_fma_f32 v[146:147], v[58:59], v[142:143], v[26:27] op_sel_hi:[1,0,1]
	v_pk_fma_f32 v[144:145], v[56:57], v[142:143], v[24:25] op_sel_hi:[1,0,1]
	s_cbranch_vccnz .LBB0_198
	s_add_i32 s0, s61, -6
	s_cmp_gt_u32 s0, 2
	s_cselect_b64 s[0:1], -1, 0
	s_xor_b64 s[36:37], s[34:35], -1
	s_and_b64 s[0:1], s[36:37], s[0:1]
	s_and_b64 vcc, exec, s[0:1]
	s_cbranch_vccnz .LBB0_198
	v_mbcnt_hi_u32_b32 v141, -1, v207
	v_and_b32_e32 v160, 64, v141
	v_xor_b32_e32 v143, 16, v141
	v_add_u32_e32 v160, 64, v160
	v_cmp_lt_i32_e32 vcc, v143, v160
	s_nop 1
	v_cndmask_b32_e32 v141, v141, v143, vcc
	v_lshlrev_b32_e32 v141, 2, v141
	ds_bpermute_b32 v194, v141, v148
	ds_bpermute_b32 v190, v141, v144
	ds_bpermute_b32 v195, v141, v149
	ds_bpermute_b32 v191, v141, v145
	ds_bpermute_b32 v196, v141, v150
	ds_bpermute_b32 v192, v141, v146
	ds_bpermute_b32 v197, v141, v151
	ds_bpermute_b32 v193, v141, v147
	s_and_saveexec_b64 s[0:1], s[40:41]
	s_cbranch_execz .LBB0_197
	s_waitcnt lgkmcnt(1)
	v_pk_mul_f32 v[160:161], v[220:221], v[196:197]
	v_pk_mul_f32 v[162:163], v[218:219], v[194:195]
	s_waitcnt lgkmcnt(0)
	v_pk_mul_f32 v[164:165], v[224:225], v[192:193]
	v_pk_mul_f32 v[190:191], v[222:223], v[190:191]
	v_pk_mul_f32 v[162:163], v[174:175], v[162:163]
	v_pk_mul_f32 v[160:161], v[176:177], v[160:161]
	v_pk_mul_f32 v[190:191], v[174:175], v[190:191]
	v_pk_mul_f32 v[164:165], v[176:177], v[164:165]
	v_pk_fma_f32 v[150:151], v[150:151], v[228:229], v[160:161]
	v_pk_fma_f32 v[148:149], v[148:149], v[226:227], v[162:163]
	v_pk_fma_f32 v[146:147], v[146:147], v[232:233], v[164:165]
	v_pk_fma_f32 v[144:145], v[144:145], v[230:231], v[190:191]

.LBB0_198:
	v_pk_mul_f32 v[150:151], v[138:139], v[150:151]
	v_pk_mul_f32 v[138:139], v[138:139], v[146:147]
	v_pk_mul_f32 v[146:147], v[186:187], v[144:145]
	v_mov_b32_e32 v143, v142
	v_mad_i64_i32 v[140:141], s[0:1], s30, v140, 0
	v_pk_mul_f32 v[148:149], v[186:187], v[148:149]
	v_cvt_pk_bf16_f32 v146, v146, v147
	v_cvt_pk_bf16_f32 v147, v138, v139
	v_mov_b32_e32 v138, v142
	v_mov_b32_e32 v139, v142
	v_lshl_add_u64 v[140:141], v[140:141], 1, v[188:189]
	v_cvt_pk_bf16_f32 v144, v148, v149
	v_cvt_pk_bf16_f32 v145, v150, v151
	v_pk_fma_f32 v[134:135], v[134:135], v[138:139], v[110:111]
	v_pk_fma_f32 v[132:133], v[132:133], v[142:143], v[108:109]
	v_pk_fma_f32 v[138:139], v[130:131], v[138:139], v[106:107]
	s_and_b64 vcc, exec, s[46:47]
	v_pk_fma_f32 v[128:129], v[128:129], v[142:143], v[104:105]
	global_store_dwordx4 v[140:141], v[144:147], off
	s_cbranch_vccnz .LBB0_202
	v_mbcnt_hi_u32_b32 v130, -1, v207
	v_and_b32_e32 v142, 64, v130
	v_xor_b32_e32 v131, 16, v130
	v_add_u32_e32 v142, 64, v142
	v_cmp_lt_i32_e32 vcc, v131, v142
	s_nop 1
	v_cndmask_b32_e32 v130, v130, v131, vcc
	v_lshlrev_b32_e32 v143, 2, v130
	ds_bpermute_b32 v144, v143, v132
	ds_bpermute_b32 v130, v143, v128
	ds_bpermute_b32 v145, v143, v133
	ds_bpermute_b32 v131, v143, v129
	ds_bpermute_b32 v146, v143, v134
	ds_bpermute_b32 v142, v143, v138
	ds_bpermute_b32 v147, v143, v135
	ds_bpermute_b32 v143, v143, v139
	s_and_saveexec_b64 s[0:1], s[40:41]
	s_cbranch_execz .LBB0_201
	s_waitcnt lgkmcnt(8)
	s_waitcnt lgkmcnt(1)
	v_pk_mul_f32 v[136:137], v[220:221], v[146:147]
	v_pk_mul_f32 v[144:145], v[218:219], v[144:145]
	s_waitcnt lgkmcnt(0)
	v_pk_mul_f32 v[142:143], v[224:225], v[142:143]
	v_pk_mul_f32 v[130:131], v[222:223], v[130:131]
	v_pk_mul_f32 v[144:145], v[174:175], v[144:145]
	v_pk_mul_f32 v[136:137], v[176:177], v[136:137]
	v_pk_mul_f32 v[130:131], v[174:175], v[130:131]
	v_pk_mul_f32 v[142:143], v[176:177], v[142:143]
	v_pk_fma_f32 v[134:135], v[134:135], v[228:229], v[136:137]
	v_pk_fma_f32 v[132:133], v[132:133], v[226:227], v[144:145]
	v_pk_fma_f32 v[138:139], v[138:139], v[232:233], v[142:143]
	v_pk_fma_f32 v[128:129], v[128:129], v[230:231], v[130:131]

.LBB0_202:
	s_waitcnt lgkmcnt(6)
	v_mov_b32_e32 v130, v186
	s_waitcnt lgkmcnt(4)
	v_mov_b32_e32 v131, v186
	v_pk_mul_f32 v[134:135], v[130:131], v[134:135]
	v_pk_mul_f32 v[132:133], v[186:187], v[132:133]
	v_pk_mul_f32 v[136:137], v[130:131], v[138:139]
	v_pk_mul_f32 v[128:129], v[186:187], v[128:129]
	v_cvt_pk_bf16_f32 v132, v132, v133
	v_cvt_pk_bf16_f32 v133, v134, v135
	v_cvt_pk_bf16_f32 v134, v128, v129
	v_cvt_pk_bf16_f32 v135, v136, v137
	global_store_dwordx4 v[140:141], v[132:135], off offset:256
	s_and_b64 vcc, exec, s[44:45]
	s_nop 0
	v_add_u32_e32 v132, 48, v184
	v_ashrrev_i32_e32 v133, 31, v132
	v_lshlrev_b64 v[128:129], 6, v[132:133]
	s_waitcnt lgkmcnt(1)
	v_lshl_add_u64 v[146:147], s[12:13], 0, v[128:129]
	global_load_dwordx4 v[218:221], v128, s[14:15] offset:32
	global_load_dwordx4 v[222:225], v128, s[14:15] offset:48
	global_load_dwordx4 v[226:229], v128, s[14:15]
	global_load_dwordx4 v[230:233], v128, s[14:15] offset:16
	global_load_dwordx4 v[134:137], v[146:147], off
	global_load_dwordx4 v[138:141], v[146:147], off offset:32
	s_waitcnt lgkmcnt(0)
	global_load_dwordx4 v[142:145], v[146:147], off offset:16
	s_nop 0
	global_load_dwordx4 v[146:149], v[146:147], off offset:48
	s_waitcnt vmcnt(3)
	v_mov_b32_e32 v150, v134
	s_waitcnt vmcnt(2)
	v_mov_b32_e32 v151, v138
	v_mov_b32_e32 v138, v135
	v_mov_b32_e32 v134, v136
	v_mov_b32_e32 v135, v140
	v_mov_b32_e32 v140, v137
	s_waitcnt vmcnt(1)
	v_mov_b32_e32 v136, v142
	s_waitcnt vmcnt(0)
	v_mov_b32_e32 v137, v146
	v_mov_b32_e32 v146, v143
	v_mov_b32_e32 v142, v144
	v_mov_b32_e32 v143, v148
	v_mov_b32_e32 v148, v145
	v_pk_add_f32 v[138:139], v[150:151], v[138:139]
	v_pk_add_f32 v[134:135], v[134:135], v[140:141]
	v_pk_add_f32 v[136:137], v[136:137], v[146:147]
	v_pk_add_f32 v[140:141], v[142:143], v[148:149]
	v_pk_add_f32 v[134:135], v[138:139], v[134:135]
	v_pk_add_f32 v[136:137], v[136:137], v[140:141]
	s_nop 0
	v_pk_add_f32 v[134:135], v[134:135], v[136:137]
	s_nop 0
	v_add_f32_e32 v133, v134, v135
	v_fmamk_f32 v133, v133, 0x3a800000, v208
	v_mul_f32_e32 v134, 0x4b800000, v133
	v_cmp_gt_f32_e64 s[0:1], s94, v133
	s_nop 1
	v_cndmask_b32_e64 v133, v133, v134, s[0:1]
	v_rsq_f32_e32 v133, v133
	s_nop 0
	v_mul_f32_e32 v134, 0x45800000, v133
	v_cndmask_b32_e64 v134, v133, v134, s[0:1]
	v_pk_fma_f32 v[142:143], v[54:55], v[134:135], v[30:31] op_sel_hi:[1,0,1]
	v_pk_fma_f32 v[140:141], v[52:53], v[134:135], v[28:29] op_sel_hi:[1,0,1]
	v_pk_fma_f32 v[138:139], v[50:51], v[134:135], v[26:27] op_sel_hi:[1,0,1]
	v_pk_fma_f32 v[136:137], v[48:49], v[134:135], v[24:25] op_sel_hi:[1,0,1]
	s_cbranch_vccnz .LBB0_207
	s_add_i32 s0, s61, -6
	s_cmp_gt_u32 s0, 2
	s_cselect_b64 s[0:1], -1, 0
	s_xor_b64 s[36:37], s[34:35], -1
	s_and_b64 s[0:1], s[36:37], s[0:1]
	s_and_b64 vcc, exec, s[0:1]
	s_cbranch_vccnz .LBB0_207
	v_mbcnt_hi_u32_b32 v133, -1, v207
	v_and_b32_e32 v144, 64, v133
	v_xor_b32_e32 v135, 16, v133
	v_add_u32_e32 v144, 64, v144
	v_cmp_lt_i32_e32 vcc, v135, v144
	s_nop 1
	v_cndmask_b32_e32 v133, v133, v135, vcc
	v_lshlrev_b32_e32 v133, 2, v133
	ds_bpermute_b32 v148, v133, v140
	ds_bpermute_b32 v144, v133, v136
	ds_bpermute_b32 v149, v133, v141
	ds_bpermute_b32 v145, v133, v137
	ds_bpermute_b32 v150, v133, v142
	ds_bpermute_b32 v146, v133, v138
	ds_bpermute_b32 v151, v133, v143
	ds_bpermute_b32 v147, v133, v139
	s_and_saveexec_b64 s[0:1], s[40:41]
	s_cbranch_execz .LBB0_206
	s_waitcnt lgkmcnt(1)
	v_pk_mul_f32 v[150:151], v[220:221], v[150:151]
	v_pk_mul_f32 v[148:149], v[218:219], v[148:149]
	s_waitcnt lgkmcnt(0)
	v_pk_mul_f32 v[146:147], v[224:225], v[146:147]
	v_pk_mul_f32 v[144:145], v[222:223], v[144:145]
	v_pk_mul_f32 v[148:149], v[174:175], v[148:149]
	v_pk_mul_f32 v[150:151], v[176:177], v[150:151]
	v_pk_mul_f32 v[144:145], v[174:175], v[144:145]
	v_pk_mul_f32 v[146:147], v[176:177], v[146:147]
	v_pk_fma_f32 v[142:143], v[142:143], v[228:229], v[150:151]
	v_pk_fma_f32 v[140:141], v[140:141], v[226:227], v[148:149]
	v_pk_fma_f32 v[138:139], v[138:139], v[232:233], v[146:147]
	v_pk_fma_f32 v[136:137], v[136:137], v[230:231], v[144:145]

.LBB0_207:
	v_pk_mul_f32 v[142:143], v[130:131], v[142:143]
	v_pk_mul_f32 v[130:131], v[130:131], v[138:139]
	v_pk_mul_f32 v[138:139], v[186:187], v[136:137]
	v_mov_b32_e32 v135, v134
	v_mad_i64_i32 v[132:133], s[0:1], s30, v132, 0
	v_pk_mul_f32 v[140:141], v[186:187], v[140:141]
	v_cvt_pk_bf16_f32 v138, v138, v139
	v_cvt_pk_bf16_f32 v139, v130, v131
	v_mov_b32_e32 v130, v134
	v_mov_b32_e32 v131, v134
	v_lshl_add_u64 v[132:133], v[132:133], 1, v[188:189]
	v_cvt_pk_bf16_f32 v136, v140, v141
	v_cvt_pk_bf16_f32 v137, v142, v143
	v_pk_fma_f32 v[126:127], v[126:127], v[130:131], v[110:111]
	v_pk_fma_f32 v[124:125], v[124:125], v[134:135], v[108:109]
	v_pk_fma_f32 v[130:131], v[122:123], v[130:131], v[106:107]
	s_and_b64 vcc, exec, s[46:47]
	v_pk_fma_f32 v[120:121], v[120:121], v[134:135], v[104:105]
	global_store_dwordx4 v[132:133], v[136:139], off
	s_cbranch_vccnz .LBB0_211
	v_mbcnt_hi_u32_b32 v122, -1, v207
	v_and_b32_e32 v134, 64, v122
	v_xor_b32_e32 v123, 16, v122
	v_add_u32_e32 v134, 64, v134
	v_cmp_lt_i32_e32 vcc, v123, v134
	s_nop 1
	v_cndmask_b32_e32 v122, v122, v123, vcc
	v_lshlrev_b32_e32 v135, 2, v122
	ds_bpermute_b32 v136, v135, v124
	ds_bpermute_b32 v122, v135, v120
	ds_bpermute_b32 v137, v135, v125
	ds_bpermute_b32 v123, v135, v121
	ds_bpermute_b32 v138, v135, v126
	ds_bpermute_b32 v134, v135, v130
	ds_bpermute_b32 v139, v135, v127
	ds_bpermute_b32 v135, v135, v131
	s_and_saveexec_b64 s[0:1], s[40:41]
	s_cbranch_execz .LBB0_210
	s_waitcnt lgkmcnt(8)
	s_waitcnt lgkmcnt(1)
	v_pk_mul_f32 v[128:129], v[220:221], v[138:139]
	v_pk_mul_f32 v[136:137], v[218:219], v[136:137]
	s_waitcnt lgkmcnt(0)
	v_pk_mul_f32 v[134:135], v[224:225], v[134:135]
	v_pk_mul_f32 v[122:123], v[222:223], v[122:123]
	v_pk_mul_f32 v[136:137], v[174:175], v[136:137]
	v_pk_mul_f32 v[128:129], v[176:177], v[128:129]
	v_pk_mul_f32 v[122:123], v[174:175], v[122:123]
	v_pk_mul_f32 v[134:135], v[176:177], v[134:135]
	v_pk_fma_f32 v[126:127], v[126:127], v[228:229], v[128:129]
	v_pk_fma_f32 v[124:125], v[124:125], v[226:227], v[136:137]
	v_pk_fma_f32 v[130:131], v[130:131], v[232:233], v[134:135]
	v_pk_fma_f32 v[120:121], v[120:121], v[230:231], v[122:123]

.LBB0_211:
	s_waitcnt lgkmcnt(6)
	v_mov_b32_e32 v122, v186
	s_waitcnt lgkmcnt(4)
	v_mov_b32_e32 v123, v186
	v_pk_mul_f32 v[126:127], v[122:123], v[126:127]
	v_pk_mul_f32 v[124:125], v[186:187], v[124:125]
	v_pk_mul_f32 v[128:129], v[122:123], v[130:131]
	v_pk_mul_f32 v[120:121], v[186:187], v[120:121]
	v_cvt_pk_bf16_f32 v124, v124, v125
	v_cvt_pk_bf16_f32 v125, v126, v127
	v_cvt_pk_bf16_f32 v126, v120, v121
	v_cvt_pk_bf16_f32 v127, v128, v129
	global_store_dwordx4 v[132:133], v[124:127], off offset:256
	s_and_b64 vcc, exec, s[44:45]
	s_nop 0
	v_add_u32_e32 v124, 0x80, v184
	v_ashrrev_i32_e32 v125, 31, v124
	v_lshlrev_b64 v[120:121], 6, v[124:125]
	s_waitcnt lgkmcnt(1)
	v_lshl_add_u64 v[138:139], s[12:13], 0, v[120:121]
	global_load_dwordx4 v[218:221], v120, s[14:15] offset:32
	global_load_dwordx4 v[222:225], v120, s[14:15] offset:48
	global_load_dwordx4 v[226:229], v120, s[14:15]
	global_load_dwordx4 v[230:233], v120, s[14:15] offset:16
	global_load_dwordx4 v[126:129], v[138:139], off
	global_load_dwordx4 v[130:133], v[138:139], off offset:32
	s_waitcnt lgkmcnt(0)
	global_load_dwordx4 v[134:137], v[138:139], off offset:16
	s_nop 0
	global_load_dwordx4 v[138:141], v[138:139], off offset:48
	s_waitcnt vmcnt(3)
	v_mov_b32_e32 v142, v126
	s_waitcnt vmcnt(2)
	v_mov_b32_e32 v143, v130
	v_mov_b32_e32 v130, v127
	v_mov_b32_e32 v126, v128
	v_mov_b32_e32 v127, v132
	v_mov_b32_e32 v132, v129
	s_waitcnt vmcnt(1)
	v_mov_b32_e32 v128, v134
	s_waitcnt vmcnt(0)
	v_mov_b32_e32 v129, v138
	v_mov_b32_e32 v138, v135
	v_mov_b32_e32 v134, v136
	v_mov_b32_e32 v135, v140
	v_mov_b32_e32 v140, v137
	v_pk_add_f32 v[130:131], v[142:143], v[130:131]
	v_pk_add_f32 v[126:127], v[126:127], v[132:133]
	v_pk_add_f32 v[128:129], v[128:129], v[138:139]
	v_pk_add_f32 v[132:133], v[134:135], v[140:141]
	v_pk_add_f32 v[126:127], v[130:131], v[126:127]
	v_pk_add_f32 v[128:129], v[128:129], v[132:133]
	s_nop 0
	v_pk_add_f32 v[126:127], v[126:127], v[128:129]
	s_nop 0
	v_add_f32_e32 v125, v126, v127
	v_fmamk_f32 v125, v125, 0x3a800000, v208
	v_mul_f32_e32 v126, 0x4b800000, v125
	v_cmp_gt_f32_e64 s[0:1], s94, v125
	s_nop 1
	v_cndmask_b32_e64 v125, v125, v126, s[0:1]
	v_rsq_f32_e32 v125, v125
	s_nop 0
	v_mul_f32_e32 v126, 0x45800000, v125
	v_cndmask_b32_e64 v126, v125, v126, s[0:1]
	v_pk_fma_f32 v[134:135], v[46:47], v[126:127], v[30:31] op_sel_hi:[1,0,1]
	v_pk_fma_f32 v[132:133], v[44:45], v[126:127], v[28:29] op_sel_hi:[1,0,1]
	v_pk_fma_f32 v[130:131], v[42:43], v[126:127], v[26:27] op_sel_hi:[1,0,1]
	v_pk_fma_f32 v[128:129], v[40:41], v[126:127], v[24:25] op_sel_hi:[1,0,1]
	s_cbranch_vccnz .LBB0_216
	s_add_i32 s0, s61, -6
	s_cmp_gt_u32 s0, 2
	s_cselect_b64 s[0:1], -1, 0
	s_xor_b64 s[36:37], s[34:35], -1
	s_and_b64 s[0:1], s[36:37], s[0:1]
	s_and_b64 vcc, exec, s[0:1]
	s_cbranch_vccnz .LBB0_216
	v_mbcnt_hi_u32_b32 v125, -1, v207
	v_and_b32_e32 v136, 64, v125
	v_xor_b32_e32 v127, 16, v125
	v_add_u32_e32 v136, 64, v136
	v_cmp_lt_i32_e32 vcc, v127, v136
	s_nop 1
	v_cndmask_b32_e32 v125, v125, v127, vcc
	v_lshlrev_b32_e32 v125, 2, v125
	ds_bpermute_b32 v140, v125, v132
	ds_bpermute_b32 v136, v125, v128
	ds_bpermute_b32 v141, v125, v133
	ds_bpermute_b32 v137, v125, v129
	ds_bpermute_b32 v142, v125, v134
	ds_bpermute_b32 v138, v125, v130
	ds_bpermute_b32 v143, v125, v135
	ds_bpermute_b32 v139, v125, v131
	s_and_saveexec_b64 s[0:1], s[40:41]
	s_cbranch_execz .LBB0_215
	s_waitcnt lgkmcnt(1)
	v_pk_mul_f32 v[142:143], v[220:221], v[142:143]
	v_pk_mul_f32 v[140:141], v[218:219], v[140:141]
	s_waitcnt lgkmcnt(0)
	v_pk_mul_f32 v[138:139], v[224:225], v[138:139]
	v_pk_mul_f32 v[136:137], v[222:223], v[136:137]
	v_pk_mul_f32 v[140:141], v[174:175], v[140:141]
	v_pk_mul_f32 v[142:143], v[176:177], v[142:143]
	v_pk_mul_f32 v[136:137], v[174:175], v[136:137]
	v_pk_mul_f32 v[138:139], v[176:177], v[138:139]
	v_pk_fma_f32 v[134:135], v[134:135], v[228:229], v[142:143]
	v_pk_fma_f32 v[132:133], v[132:133], v[226:227], v[140:141]
	v_pk_fma_f32 v[130:131], v[130:131], v[232:233], v[138:139]
	v_pk_fma_f32 v[128:129], v[128:129], v[230:231], v[136:137]

.LBB0_216:
	v_pk_mul_f32 v[134:135], v[122:123], v[134:135]
	v_pk_mul_f32 v[122:123], v[122:123], v[130:131]
	v_pk_mul_f32 v[130:131], v[186:187], v[128:129]
	v_mov_b32_e32 v127, v126
	v_mad_i64_i32 v[124:125], s[0:1], s30, v124, 0
	v_pk_mul_f32 v[132:133], v[186:187], v[132:133]
	v_cvt_pk_bf16_f32 v130, v130, v131
	v_cvt_pk_bf16_f32 v131, v122, v123
	v_mov_b32_e32 v122, v126
	v_mov_b32_e32 v123, v126
	v_lshl_add_u64 v[124:125], v[124:125], 1, v[188:189]
	v_cvt_pk_bf16_f32 v128, v132, v133
	v_cvt_pk_bf16_f32 v129, v134, v135
	v_pk_fma_f32 v[118:119], v[118:119], v[122:123], v[110:111]
	v_pk_fma_f32 v[116:117], v[116:117], v[126:127], v[108:109]
	v_pk_fma_f32 v[122:123], v[114:115], v[122:123], v[106:107]
	s_and_b64 vcc, exec, s[46:47]
	v_pk_fma_f32 v[112:113], v[112:113], v[126:127], v[104:105]
	global_store_dwordx4 v[124:125], v[128:131], off
	s_cbranch_vccnz .LBB0_220
	v_mbcnt_hi_u32_b32 v114, -1, v207
	v_and_b32_e32 v126, 64, v114
	v_xor_b32_e32 v115, 16, v114
	v_add_u32_e32 v126, 64, v126
	v_cmp_lt_i32_e32 vcc, v115, v126
	s_nop 1
	v_cndmask_b32_e32 v114, v114, v115, vcc
	v_lshlrev_b32_e32 v127, 2, v114
	ds_bpermute_b32 v128, v127, v116
	ds_bpermute_b32 v114, v127, v112
	ds_bpermute_b32 v129, v127, v117
	ds_bpermute_b32 v115, v127, v113
	ds_bpermute_b32 v130, v127, v118
	ds_bpermute_b32 v126, v127, v122
	ds_bpermute_b32 v131, v127, v119
	ds_bpermute_b32 v127, v127, v123
	s_and_saveexec_b64 s[0:1], s[40:41]
	s_cbranch_execz .LBB0_219
	s_waitcnt lgkmcnt(8)
	s_waitcnt lgkmcnt(1)
	v_pk_mul_f32 v[120:121], v[220:221], v[130:131]
	v_pk_mul_f32 v[128:129], v[218:219], v[128:129]
	s_waitcnt lgkmcnt(0)
	v_pk_mul_f32 v[126:127], v[224:225], v[126:127]
	v_pk_mul_f32 v[114:115], v[222:223], v[114:115]
	v_pk_mul_f32 v[128:129], v[174:175], v[128:129]
	v_pk_mul_f32 v[120:121], v[176:177], v[120:121]
	v_pk_mul_f32 v[114:115], v[174:175], v[114:115]
	v_pk_mul_f32 v[126:127], v[176:177], v[126:127]
	v_pk_fma_f32 v[118:119], v[118:119], v[228:229], v[120:121]
	v_pk_fma_f32 v[116:117], v[116:117], v[226:227], v[128:129]
	v_pk_fma_f32 v[122:123], v[122:123], v[232:233], v[126:127]
	v_pk_fma_f32 v[112:113], v[112:113], v[230:231], v[114:115]

.LBB0_220:
	s_waitcnt lgkmcnt(6)
	v_mov_b32_e32 v114, v186
	s_waitcnt lgkmcnt(4)
	v_mov_b32_e32 v115, v186
	v_pk_mul_f32 v[118:119], v[114:115], v[118:119]
	v_pk_mul_f32 v[116:117], v[186:187], v[116:117]
	v_pk_mul_f32 v[120:121], v[114:115], v[122:123]
	v_pk_mul_f32 v[112:113], v[186:187], v[112:113]
	v_cvt_pk_bf16_f32 v116, v116, v117
	v_cvt_pk_bf16_f32 v117, v118, v119
	v_cvt_pk_bf16_f32 v118, v112, v113
	v_cvt_pk_bf16_f32 v119, v120, v121
	global_store_dwordx4 v[124:125], v[116:119], off offset:256
	s_and_b64 vcc, exec, s[44:45]
	s_nop 0
	v_add_u32_e32 v116, 0x90, v184
	v_ashrrev_i32_e32 v117, 31, v116
	v_lshlrev_b64 v[112:113], 6, v[116:117]
	s_waitcnt lgkmcnt(1)
	v_lshl_add_u64 v[130:131], s[12:13], 0, v[112:113]
	global_load_dwordx4 v[218:221], v112, s[14:15] offset:32
	global_load_dwordx4 v[222:225], v112, s[14:15] offset:48
	global_load_dwordx4 v[226:229], v112, s[14:15]
	global_load_dwordx4 v[230:233], v112, s[14:15] offset:16
	global_load_dwordx4 v[118:121], v[130:131], off
	global_load_dwordx4 v[122:125], v[130:131], off offset:32
	s_waitcnt lgkmcnt(0)
	global_load_dwordx4 v[126:129], v[130:131], off offset:16
	s_nop 0
	global_load_dwordx4 v[130:133], v[130:131], off offset:48
	s_waitcnt vmcnt(3)
	v_mov_b32_e32 v134, v118
	s_waitcnt vmcnt(2)
	v_mov_b32_e32 v135, v122
	v_mov_b32_e32 v122, v119
	v_mov_b32_e32 v118, v120
	v_mov_b32_e32 v119, v124
	v_mov_b32_e32 v124, v121
	s_waitcnt vmcnt(1)
	v_mov_b32_e32 v120, v126
	s_waitcnt vmcnt(0)
	v_mov_b32_e32 v121, v130
	v_mov_b32_e32 v130, v127
	v_mov_b32_e32 v126, v128
	v_mov_b32_e32 v127, v132
	v_mov_b32_e32 v132, v129
	v_pk_add_f32 v[122:123], v[134:135], v[122:123]
	v_pk_add_f32 v[118:119], v[118:119], v[124:125]
	v_pk_add_f32 v[120:121], v[120:121], v[130:131]
	v_pk_add_f32 v[124:125], v[126:127], v[132:133]
	v_pk_add_f32 v[118:119], v[122:123], v[118:119]
	v_pk_add_f32 v[120:121], v[120:121], v[124:125]
	s_nop 0
	v_pk_add_f32 v[118:119], v[118:119], v[120:121]
	s_nop 0
	v_add_f32_e32 v117, v118, v119
	v_fmamk_f32 v117, v117, 0x3a800000, v208
	v_mul_f32_e32 v118, 0x4b800000, v117
	v_cmp_gt_f32_e64 s[0:1], s94, v117
	s_nop 1
	v_cndmask_b32_e64 v117, v117, v118, s[0:1]
	v_rsq_f32_e32 v117, v117
	s_nop 0
	v_mul_f32_e32 v118, 0x45800000, v117
	v_cndmask_b32_e64 v118, v117, v118, s[0:1]
	v_pk_fma_f32 v[126:127], v[38:39], v[118:119], v[30:31] op_sel_hi:[1,0,1]
	v_pk_fma_f32 v[124:125], v[36:37], v[118:119], v[28:29] op_sel_hi:[1,0,1]
	v_pk_fma_f32 v[122:123], v[34:35], v[118:119], v[26:27] op_sel_hi:[1,0,1]
	v_pk_fma_f32 v[120:121], v[32:33], v[118:119], v[24:25] op_sel_hi:[1,0,1]
	s_cbranch_vccnz .LBB0_225
	s_add_i32 s0, s61, -6
	s_cmp_gt_u32 s0, 2
	s_cselect_b64 s[0:1], -1, 0
	s_xor_b64 s[36:37], s[34:35], -1
	s_and_b64 s[0:1], s[36:37], s[0:1]
	s_and_b64 vcc, exec, s[0:1]
	s_cbranch_vccnz .LBB0_225
	v_mbcnt_hi_u32_b32 v117, -1, v207
	v_and_b32_e32 v128, 64, v117
	v_xor_b32_e32 v119, 16, v117
	v_add_u32_e32 v128, 64, v128
	v_cmp_lt_i32_e32 vcc, v119, v128
	s_nop 1
	v_cndmask_b32_e32 v117, v117, v119, vcc
	v_lshlrev_b32_e32 v117, 2, v117
	ds_bpermute_b32 v132, v117, v124
	ds_bpermute_b32 v128, v117, v120
	ds_bpermute_b32 v133, v117, v125
	ds_bpermute_b32 v129, v117, v121
	ds_bpermute_b32 v134, v117, v126
	ds_bpermute_b32 v130, v117, v122
	ds_bpermute_b32 v135, v117, v127
	ds_bpermute_b32 v131, v117, v123
	s_and_saveexec_b64 s[0:1], s[40:41]
	s_cbranch_execz .LBB0_224
	s_nop 0
	s_waitcnt lgkmcnt(1)
	v_pk_mul_f32 v[134:135], v[220:221], v[134:135]
	v_pk_mul_f32 v[132:133], v[218:219], v[132:133]
	s_waitcnt lgkmcnt(0)
	v_pk_mul_f32 v[130:131], v[224:225], v[130:131]
	v_pk_mul_f32 v[128:129], v[222:223], v[128:129]
	v_pk_mul_f32 v[132:133], v[174:175], v[132:133]
	v_pk_mul_f32 v[134:135], v[176:177], v[134:135]
	v_pk_mul_f32 v[128:129], v[174:175], v[128:129]
	v_pk_mul_f32 v[130:131], v[176:177], v[130:131]
	v_pk_fma_f32 v[126:127], v[126:127], v[228:229], v[134:135]
	v_pk_fma_f32 v[124:125], v[124:125], v[226:227], v[132:133]
	v_pk_fma_f32 v[122:123], v[122:123], v[232:233], v[130:131]
	v_pk_fma_f32 v[120:121], v[120:121], v[230:231], v[128:129]

.LBB0_225:
	v_pk_mul_f32 v[126:127], v[114:115], v[126:127]
	v_pk_mul_f32 v[114:115], v[114:115], v[122:123]
	v_pk_mul_f32 v[122:123], v[186:187], v[120:121]
	v_mov_b32_e32 v119, v118
	v_mad_i64_i32 v[116:117], s[0:1], s30, v116, 0
	v_pk_mul_f32 v[124:125], v[186:187], v[124:125]
	v_cvt_pk_bf16_f32 v122, v122, v123
	v_cvt_pk_bf16_f32 v123, v114, v115
	v_mov_b32_e32 v114, v118
	v_mov_b32_e32 v115, v118
	v_lshl_add_u64 v[116:117], v[116:117], 1, v[188:189]
	v_cvt_pk_bf16_f32 v120, v124, v125
	v_cvt_pk_bf16_f32 v121, v126, v127
	v_pk_fma_f32 v[102:103], v[102:103], v[114:115], v[110:111]
	v_pk_fma_f32 v[100:101], v[100:101], v[118:119], v[108:109]
	v_pk_fma_f32 v[114:115], v[98:99], v[114:115], v[106:107]
	s_and_b64 vcc, exec, s[46:47]
	v_pk_fma_f32 v[96:97], v[96:97], v[118:119], v[104:105]
	global_store_dwordx4 v[116:117], v[120:123], off
	s_cbranch_vccnz .LBB0_229
	v_mbcnt_hi_u32_b32 v98, -1, v207
	v_and_b32_e32 v118, 64, v98
	v_xor_b32_e32 v99, 16, v98
	v_add_u32_e32 v118, 64, v118
	v_cmp_lt_i32_e32 vcc, v99, v118
	s_nop 1
	v_cndmask_b32_e32 v98, v98, v99, vcc
	v_lshlrev_b32_e32 v119, 2, v98
	ds_bpermute_b32 v120, v119, v100
	ds_bpermute_b32 v98, v119, v96
	ds_bpermute_b32 v121, v119, v101
	ds_bpermute_b32 v99, v119, v97
	ds_bpermute_b32 v122, v119, v102
	ds_bpermute_b32 v118, v119, v114
	ds_bpermute_b32 v123, v119, v103
	ds_bpermute_b32 v119, v119, v115
	s_and_saveexec_b64 s[0:1], s[40:41]
	s_cbranch_execz .LBB0_228
	s_waitcnt lgkmcnt(8)
	s_waitcnt lgkmcnt(1)
	v_pk_mul_f32 v[112:113], v[220:221], v[122:123]
	v_pk_mul_f32 v[120:121], v[218:219], v[120:121]
	s_waitcnt lgkmcnt(0)
	v_pk_mul_f32 v[118:119], v[224:225], v[118:119]
	v_pk_mul_f32 v[98:99], v[222:223], v[98:99]
	v_pk_mul_f32 v[120:121], v[174:175], v[120:121]
	v_pk_mul_f32 v[112:113], v[176:177], v[112:113]
	v_pk_mul_f32 v[98:99], v[174:175], v[98:99]
	v_pk_mul_f32 v[118:119], v[176:177], v[118:119]
	v_pk_fma_f32 v[102:103], v[102:103], v[228:229], v[112:113]
	v_pk_fma_f32 v[100:101], v[100:101], v[226:227], v[120:121]
	v_pk_fma_f32 v[114:115], v[114:115], v[232:233], v[118:119]
	v_pk_fma_f32 v[96:97], v[96:97], v[230:231], v[98:99]

.LBB0_229:
	s_waitcnt lgkmcnt(6)
	v_mov_b32_e32 v98, v186
	s_waitcnt lgkmcnt(4)
	v_mov_b32_e32 v99, v186
	v_pk_mul_f32 v[102:103], v[98:99], v[102:103]
	v_pk_mul_f32 v[100:101], v[186:187], v[100:101]
	v_pk_mul_f32 v[112:113], v[98:99], v[114:115]
	v_pk_mul_f32 v[96:97], v[186:187], v[96:97]
	v_cvt_pk_bf16_f32 v100, v100, v101
	v_cvt_pk_bf16_f32 v101, v102, v103
	v_cvt_pk_bf16_f32 v102, v96, v97
	v_cvt_pk_bf16_f32 v103, v112, v113
	global_store_dwordx4 v[116:117], v[100:103], off offset:256
	s_and_b64 vcc, exec, s[44:45]
	s_nop 0
	v_add_u32_e32 v100, 0xa0, v184
	v_ashrrev_i32_e32 v101, 31, v100
	v_lshlrev_b64 v[96:97], 6, v[100:101]
	v_lshl_add_u64 v[102:103], s[12:13], 0, v[96:97]
	global_load_dwordx4 v[218:221], v96, s[14:15] offset:32
	global_load_dwordx4 v[222:225], v96, s[14:15] offset:48
	global_load_dwordx4 v[226:229], v96, s[14:15]
	global_load_dwordx4 v[230:233], v96, s[14:15] offset:16
	global_load_dwordx4 v[112:115], v[102:103], off
	s_waitcnt lgkmcnt(0)
	global_load_dwordx4 v[116:119], v[102:103], off offset:32
	global_load_dwordx4 v[120:123], v[102:103], off offset:16
	global_load_dwordx4 v[124:127], v[102:103], off offset:48
	s_waitcnt vmcnt(3)
	v_mov_b32_e32 v102, v112
	s_waitcnt vmcnt(2)
	v_mov_b32_e32 v103, v116
	v_mov_b32_e32 v116, v113
	v_mov_b32_e32 v112, v114
	v_mov_b32_e32 v113, v118
	v_mov_b32_e32 v118, v115
	s_waitcnt vmcnt(1)
	v_mov_b32_e32 v114, v120
	s_waitcnt vmcnt(0)
	v_mov_b32_e32 v115, v124
	v_mov_b32_e32 v124, v121
	v_mov_b32_e32 v120, v122
	v_mov_b32_e32 v121, v126
	v_mov_b32_e32 v126, v123
	v_pk_add_f32 v[102:103], v[102:103], v[116:117]
	v_pk_add_f32 v[112:113], v[112:113], v[118:119]
	v_pk_add_f32 v[114:115], v[114:115], v[124:125]
	v_pk_add_f32 v[116:117], v[120:121], v[126:127]
	v_pk_add_f32 v[102:103], v[102:103], v[112:113]
	v_pk_add_f32 v[112:113], v[114:115], v[116:117]
	s_nop 0
	v_pk_add_f32 v[102:103], v[102:103], v[112:113]
	s_nop 0
	v_add_f32_e32 v101, v102, v103
	v_fmamk_f32 v101, v101, 0x3a800000, v208
	v_mul_f32_e32 v102, 0x4b800000, v101
	v_cmp_gt_f32_e64 s[0:1], s94, v101
	s_nop 1
	v_cndmask_b32_e64 v101, v101, v102, s[0:1]
	v_rsq_f32_e32 v101, v101
	s_nop 0
	v_mul_f32_e32 v102, 0x45800000, v101
	v_cndmask_b32_e64 v102, v101, v102, s[0:1]
	v_pk_fma_f32 v[118:119], v[22:23], v[102:103], v[30:31] op_sel_hi:[1,0,1]
	v_pk_fma_f32 v[116:117], v[20:21], v[102:103], v[28:29] op_sel_hi:[1,0,1]
	v_pk_fma_f32 v[114:115], v[18:19], v[102:103], v[26:27] op_sel_hi:[1,0,1]
	v_pk_fma_f32 v[112:113], v[16:17], v[102:103], v[24:25] op_sel_hi:[1,0,1]
	s_cbranch_vccnz .LBB0_234
	s_add_i32 s0, s61, -6
	s_cmp_gt_u32 s0, 2
	s_cselect_b64 s[0:1], -1, 0
	s_xor_b64 s[36:37], s[34:35], -1
	s_and_b64 s[0:1], s[36:37], s[0:1]
	s_and_b64 vcc, exec, s[0:1]
	s_cbranch_vccnz .LBB0_234
	v_mbcnt_hi_u32_b32 v101, -1, v207
	v_and_b32_e32 v120, 64, v101
	v_xor_b32_e32 v103, 16, v101
	v_add_u32_e32 v120, 64, v120
	v_cmp_lt_i32_e32 vcc, v103, v120
	s_nop 1
	v_cndmask_b32_e32 v101, v101, v103, vcc
	v_lshlrev_b32_e32 v101, 2, v101
	ds_bpermute_b32 v124, v101, v116
	ds_bpermute_b32 v120, v101, v112
	ds_bpermute_b32 v125, v101, v117
	ds_bpermute_b32 v121, v101, v113
	ds_bpermute_b32 v126, v101, v118
	ds_bpermute_b32 v122, v101, v114
	ds_bpermute_b32 v127, v101, v119
	ds_bpermute_b32 v123, v101, v115
	s_and_saveexec_b64 s[0:1], s[40:41]
	s_cbranch_execz .LBB0_233
	s_nop 0
	s_waitcnt lgkmcnt(1)
	v_pk_mul_f32 v[126:127], v[220:221], v[126:127]
	v_pk_mul_f32 v[124:125], v[218:219], v[124:125]
	s_waitcnt lgkmcnt(0)
	v_pk_mul_f32 v[122:123], v[224:225], v[122:123]
	v_pk_mul_f32 v[120:121], v[222:223], v[120:121]
	v_pk_mul_f32 v[124:125], v[174:175], v[124:125]
	v_pk_mul_f32 v[126:127], v[176:177], v[126:127]
	v_pk_mul_f32 v[120:121], v[174:175], v[120:121]
	v_pk_mul_f32 v[122:123], v[176:177], v[122:123]
	v_pk_fma_f32 v[118:119], v[118:119], v[228:229], v[126:127]
	v_pk_fma_f32 v[116:117], v[116:117], v[226:227], v[124:125]
	v_pk_fma_f32 v[114:115], v[114:115], v[232:233], v[122:123]
	v_pk_fma_f32 v[112:113], v[112:113], v[230:231], v[120:121]

.LBB0_234:
	v_pk_mul_f32 v[118:119], v[98:99], v[118:119]
	v_pk_mul_f32 v[98:99], v[98:99], v[114:115]
	v_pk_mul_f32 v[114:115], v[186:187], v[112:113]
	v_mov_b32_e32 v103, v102
	v_mad_i64_i32 v[100:101], s[0:1], s30, v100, 0
	v_pk_mul_f32 v[116:117], v[186:187], v[116:117]
	v_cvt_pk_bf16_f32 v114, v114, v115
	v_cvt_pk_bf16_f32 v115, v98, v99
	v_mov_b32_e32 v98, v102
	v_mov_b32_e32 v99, v102
	v_lshl_add_u64 v[100:101], v[100:101], 1, v[188:189]
	v_cvt_pk_bf16_f32 v112, v116, v117
	v_cvt_pk_bf16_f32 v113, v118, v119
	v_pk_fma_f32 v[94:95], v[94:95], v[98:99], v[110:111]
	v_pk_fma_f32 v[92:93], v[92:93], v[102:103], v[108:109]
	v_pk_fma_f32 v[98:99], v[90:91], v[98:99], v[106:107]
	s_and_b64 vcc, exec, s[46:47]
	v_pk_fma_f32 v[88:89], v[88:89], v[102:103], v[104:105]
	global_store_dwordx4 v[100:101], v[112:115], off
	s_cbranch_vccnz .LBB0_238
	v_mbcnt_hi_u32_b32 v90, -1, v207
	v_and_b32_e32 v102, 64, v90
	v_xor_b32_e32 v91, 16, v90
	v_add_u32_e32 v102, 64, v102
	v_cmp_lt_i32_e32 vcc, v91, v102
	s_nop 1
	v_cndmask_b32_e32 v90, v90, v91, vcc
	v_lshlrev_b32_e32 v103, 2, v90
	ds_bpermute_b32 v112, v103, v92
	ds_bpermute_b32 v90, v103, v88
	ds_bpermute_b32 v113, v103, v93
	ds_bpermute_b32 v91, v103, v89
	ds_bpermute_b32 v114, v103, v94
	ds_bpermute_b32 v102, v103, v98
	ds_bpermute_b32 v115, v103, v95
	ds_bpermute_b32 v103, v103, v99
	s_and_saveexec_b64 s[0:1], s[40:41]
	s_cbranch_execz .LBB0_237
	s_waitcnt lgkmcnt(8)
	s_waitcnt lgkmcnt(1)
	v_pk_mul_f32 v[96:97], v[220:221], v[114:115]
	v_pk_mul_f32 v[112:113], v[218:219], v[112:113]
	s_waitcnt lgkmcnt(0)
	v_pk_mul_f32 v[102:103], v[224:225], v[102:103]
	v_pk_mul_f32 v[90:91], v[222:223], v[90:91]
	v_pk_mul_f32 v[112:113], v[174:175], v[112:113]
	v_pk_mul_f32 v[96:97], v[176:177], v[96:97]
	v_pk_mul_f32 v[90:91], v[174:175], v[90:91]
	v_pk_mul_f32 v[102:103], v[176:177], v[102:103]
	v_pk_fma_f32 v[94:95], v[94:95], v[228:229], v[96:97]
	v_pk_fma_f32 v[92:93], v[92:93], v[226:227], v[112:113]
	v_pk_fma_f32 v[98:99], v[98:99], v[232:233], v[102:103]
	v_pk_fma_f32 v[88:89], v[88:89], v[230:231], v[90:91]

.LBB0_238:
	s_waitcnt lgkmcnt(6)
	v_mov_b32_e32 v90, v186
	s_waitcnt lgkmcnt(4)
	v_mov_b32_e32 v91, v186
	v_pk_mul_f32 v[94:95], v[90:91], v[94:95]
	v_pk_mul_f32 v[92:93], v[186:187], v[92:93]
	v_pk_mul_f32 v[96:97], v[90:91], v[98:99]
	v_pk_mul_f32 v[88:89], v[186:187], v[88:89]
	v_cvt_pk_bf16_f32 v92, v92, v93
	v_cvt_pk_bf16_f32 v93, v94, v95
	v_cvt_pk_bf16_f32 v94, v88, v89
	v_cvt_pk_bf16_f32 v95, v96, v97
	global_store_dwordx4 v[100:101], v[92:95], off offset:256
	s_and_b64 vcc, exec, s[44:45]
	s_nop 0
	v_add_u32_e32 v92, 0xb0, v184
	v_ashrrev_i32_e32 v93, 31, v92
	v_lshlrev_b64 v[88:89], 6, v[92:93]
	s_waitcnt lgkmcnt(0)
	v_lshl_add_u64 v[102:103], s[12:13], 0, v[88:89]
	global_load_dwordx4 v[218:221], v88, s[14:15] offset:32
	global_load_dwordx4 v[222:225], v88, s[14:15] offset:48
	global_load_dwordx4 v[226:229], v88, s[14:15]
	global_load_dwordx4 v[230:233], v88, s[14:15] offset:16
	global_load_dwordx4 v[94:97], v[102:103], off
	global_load_dwordx4 v[98:101], v[102:103], off offset:32
	global_load_dwordx4 v[112:115], v[102:103], off offset:16
	global_load_dwordx4 v[116:119], v[102:103], off offset:48
	s_waitcnt vmcnt(3)
	v_mov_b32_e32 v102, v94
	s_waitcnt vmcnt(2)
	v_mov_b32_e32 v103, v98
	v_mov_b32_e32 v98, v95
	v_mov_b32_e32 v94, v96
	v_mov_b32_e32 v95, v100
	v_mov_b32_e32 v100, v97
	s_waitcnt vmcnt(1)
	v_mov_b32_e32 v96, v112
	s_waitcnt vmcnt(0)
	v_mov_b32_e32 v97, v116
	v_mov_b32_e32 v116, v113
	v_mov_b32_e32 v112, v114
	v_mov_b32_e32 v113, v118
	v_mov_b32_e32 v118, v115
	v_pk_add_f32 v[98:99], v[102:103], v[98:99]
	v_pk_add_f32 v[94:95], v[94:95], v[100:101]
	v_pk_add_f32 v[96:97], v[96:97], v[116:117]
	v_pk_add_f32 v[100:101], v[112:113], v[118:119]
	v_pk_add_f32 v[94:95], v[98:99], v[94:95]
	v_pk_add_f32 v[96:97], v[96:97], v[100:101]
	s_nop 0
	v_pk_add_f32 v[94:95], v[94:95], v[96:97]
	s_nop 0
	v_add_f32_e32 v93, v94, v95
	v_fmamk_f32 v93, v93, 0x3a800000, v208
	v_mul_f32_e32 v94, 0x4b800000, v93
	v_cmp_gt_f32_e64 s[0:1], s94, v93
	s_nop 1
	v_cndmask_b32_e64 v93, v93, v94, s[0:1]
	v_rsq_f32_e32 v93, v93
	s_nop 0
	v_mul_f32_e32 v94, 0x45800000, v93
	v_cndmask_b32_e64 v94, v93, v94, s[0:1]
	v_pk_fma_f32 v[102:103], v[14:15], v[94:95], v[30:31] op_sel_hi:[1,0,1]
	v_pk_fma_f32 v[100:101], v[12:13], v[94:95], v[28:29] op_sel_hi:[1,0,1]
	v_pk_fma_f32 v[98:99], v[10:11], v[94:95], v[26:27] op_sel_hi:[1,0,1]
	v_pk_fma_f32 v[96:97], v[8:9], v[94:95], v[24:25] op_sel_hi:[1,0,1]
	s_cbranch_vccnz .LBB0_243
	s_add_i32 s61, s61, -6
	s_cmp_gt_u32 s61, 2
	s_cselect_b64 s[0:1], -1, 0
	s_xor_b64 s[34:35], s[34:35], -1
	s_and_b64 s[0:1], s[34:35], s[0:1]
	s_and_b64 vcc, exec, s[0:1]
	s_cbranch_vccnz .LBB0_243
	v_mbcnt_hi_u32_b32 v93, -1, v207
	v_and_b32_e32 v112, 64, v93
	v_xor_b32_e32 v95, 16, v93
	v_add_u32_e32 v112, 64, v112
	v_cmp_lt_i32_e32 vcc, v95, v112
	s_nop 1
	v_cndmask_b32_e32 v93, v93, v95, vcc
	v_lshlrev_b32_e32 v93, 2, v93
	ds_bpermute_b32 v116, v93, v100
	ds_bpermute_b32 v112, v93, v96
	ds_bpermute_b32 v117, v93, v101
	ds_bpermute_b32 v113, v93, v97
	ds_bpermute_b32 v118, v93, v102
	ds_bpermute_b32 v114, v93, v98
	ds_bpermute_b32 v119, v93, v103
	ds_bpermute_b32 v115, v93, v99
	s_and_saveexec_b64 s[0:1], s[40:41]
	s_cbranch_execz .LBB0_242
	s_nop 0
	s_waitcnt lgkmcnt(1)
	v_pk_mul_f32 v[118:119], v[220:221], v[118:119]
	v_pk_mul_f32 v[116:117], v[218:219], v[116:117]
	s_waitcnt lgkmcnt(0)
	v_pk_mul_f32 v[114:115], v[224:225], v[114:115]
	v_pk_mul_f32 v[112:113], v[222:223], v[112:113]
	v_pk_mul_f32 v[116:117], v[174:175], v[116:117]
	v_pk_mul_f32 v[118:119], v[176:177], v[118:119]
	v_pk_mul_f32 v[112:113], v[174:175], v[112:113]
	v_pk_mul_f32 v[114:115], v[176:177], v[114:115]
	v_pk_fma_f32 v[102:103], v[102:103], v[228:229], v[118:119]
	v_pk_fma_f32 v[100:101], v[100:101], v[226:227], v[116:117]
	v_pk_fma_f32 v[98:99], v[98:99], v[232:233], v[114:115]
	v_pk_fma_f32 v[96:97], v[96:97], v[230:231], v[112:113]

.LBB0_243:
	v_pk_mul_f32 v[102:103], v[90:91], v[102:103]
	v_pk_mul_f32 v[90:91], v[90:91], v[98:99]
	v_pk_mul_f32 v[98:99], v[186:187], v[96:97]
	v_mov_b32_e32 v95, v94
	v_mad_i64_i32 v[92:93], s[0:1], s30, v92, 0
	v_pk_mul_f32 v[100:101], v[186:187], v[100:101]
	v_cvt_pk_bf16_f32 v98, v98, v99
	v_cvt_pk_bf16_f32 v99, v90, v91
	v_mov_b32_e32 v90, v94
	v_mov_b32_e32 v91, v94
	v_lshl_add_u64 v[92:93], v[92:93], 1, v[188:189]
	v_cvt_pk_bf16_f32 v96, v100, v101
	v_cvt_pk_bf16_f32 v97, v102, v103
	v_pk_fma_f32 v[86:87], v[86:87], v[90:91], v[110:111]
	v_pk_fma_f32 v[84:85], v[84:85], v[94:95], v[108:109]
	v_pk_fma_f32 v[82:83], v[82:83], v[90:91], v[106:107]
	s_and_b64 vcc, exec, s[46:47]
	v_pk_fma_f32 v[80:81], v[80:81], v[94:95], v[104:105]
	global_store_dwordx4 v[92:93], v[96:99], off
	s_cbranch_vccnz .LBB0_247
	v_mbcnt_hi_u32_b32 v90, -1, v207
	v_and_b32_e32 v94, 64, v90
	v_xor_b32_e32 v91, 16, v90
	v_add_u32_e32 v94, 64, v94
	v_cmp_lt_i32_e32 vcc, v91, v94
	s_nop 1
	v_cndmask_b32_e32 v90, v90, v91, vcc
	v_lshlrev_b32_e32 v95, 2, v90
	ds_bpermute_b32 v96, v95, v84
	ds_bpermute_b32 v90, v95, v80
	ds_bpermute_b32 v97, v95, v85
	ds_bpermute_b32 v91, v95, v81
	ds_bpermute_b32 v98, v95, v86
	ds_bpermute_b32 v94, v95, v82
	ds_bpermute_b32 v99, v95, v87
	ds_bpermute_b32 v95, v95, v83
	s_and_saveexec_b64 s[0:1], s[40:41]
	s_mov_b64 s[46:47], 0x8000
	s_cbranch_execz .LBB0_246
	s_waitcnt lgkmcnt(8)
	s_waitcnt lgkmcnt(1)
	v_pk_mul_f32 v[88:89], v[220:221], v[98:99]
	v_pk_mul_f32 v[96:97], v[218:219], v[96:97]
	s_waitcnt lgkmcnt(0)
	v_pk_mul_f32 v[94:95], v[224:225], v[94:95]
	v_pk_mul_f32 v[90:91], v[222:223], v[90:91]
	v_pk_mul_f32 v[96:97], v[174:175], v[96:97]
	v_pk_mul_f32 v[88:89], v[176:177], v[88:89]
	v_pk_mul_f32 v[90:91], v[174:175], v[90:91]
	v_pk_mul_f32 v[94:95], v[176:177], v[94:95]
	v_pk_fma_f32 v[86:87], v[86:87], v[228:229], v[88:89]
	v_pk_fma_f32 v[84:85], v[84:85], v[226:227], v[96:97]
	v_pk_fma_f32 v[82:83], v[82:83], v[232:233], v[94:95]
	v_pk_fma_f32 v[80:81], v[80:81], v[230:231], v[90:91]
